# v105 = v102 + one static s_setprio 1 for waves 1,3,4,6 (bit0 xor bit2) over the attention phase
# baseline (speedup 1.0000x reference)
; __global__ void __launch_bounds__(NWAVES * 64, 2) mega_fwd(Args args) {
;     ...
;     if (IN(2)) {
;         const bool lv = (F.MISC[11] == 1u) && F.G == 256 && IN(0) && IN(1);
;         const int vcu2 = lv ? (int)bar.x * 32 + (int)F.MISC[10] : F.vcu;
.LBB0_315:
	s_cmp_lt_i32 s52, 3
	s_cselect_b64 s[0:1], -1, 0
	s_cmp_gt_i32 s53, 2
	s_cselect_b64 s[4:5], -1, 0
	s_and_b64 s[0:1], s[0:1], s[4:5]
	s_andn2_b64 vcc, exec, s[0:1]
	s_cbranch_vccnz .LBB0_553
	v_readfirstlane_b32 s0, v0
	s_lshr_b32 s0, s0, 6
	s_lshr_b32 s1, s0, 2
	s_xor_b32 s0, s0, s1
	s_bitcmp1_b32 s0, 0
	s_cbranch_scc0 .Lp2prio_lo
	s_setprio 1
